# E2b k=S/2 row prelude: the one-load-per-iteration loop unrolled by 4 (four 1-KB row segments in flight, same accumulation order), both even layers
# speedup vs baseline: 1.0170x; 1.0094x over previous
; __device__ __forceinline__ unsigned cvt_pk_bf16(float lo, float hi) { unsigned r; asm("v_cvt_pk_bf16_f32 %0, %1, %2" : "=v"(r) : "v"(lo), "v"(hi)); return r; }
; template <int layer>
; __device__ __forceinline__ void run_layer(LAS unsigned char* lds, const XcdBarrier& xb) {
;     ...
;                 for (int job = gw; job < 12 * 512; job += NGW) {
;                     const int seq = job >> 9, ch = job & 511;
;                     const int S = seq < 8 ? 2048 : 4096; const size_t tok0 = seq < 8 ? (size_t)seq * 2048 : (size_t)TP + (size_t)(seq - 8) * 4096;
;                     const bf16_t* fp = FT + (size_t)ch * T + tok0;
;                     float a = 0.f;
;                     for (int s0 = lane * 8; s0 < S; s0 += 512) { const u32x4 v = *(const u32x4*)(fp + s0);
; #pragma unroll
;                         for (int e = 0; e < 4; ++e) a += bf_lo(v[e]) - bf_hi(v[e]); }
;                     a = wave_sum(a) * (S == 2048 ? 0.02209708691207961f : 0.015625f);
;                     if (lane == 0) { bf16_t* o = PQ + (tok0 + S / 2) * 1024 + (ch >> 7) * 256 + (ch & 127); o[0] = (bf16_t)(cvt_pk_bf16(a, 0.f) & 0xffffu); o[128] = 0; }
;                 }
.LBB0_413:
	global_load_dwordx4 v[24:27], v[6:7], off
	global_load_dwordx4 v[32:35], v[6:7], off offset:1024
	global_load_dwordx4 v[36:39], v[6:7], off offset:2048
	global_load_dwordx4 v[40:43], v[6:7], off offset:3072
	v_add_u32_e32 v22, 0x800, v22
	v_cmp_ge_u32_e64 s[6:7], v22, v21
	v_lshl_add_u64 v[6:7], v[6:7], 0, s[24:25]
	v_lshl_add_u64 v[6:7], v[6:7], 0, s[24:25]
	v_lshl_add_u64 v[6:7], v[6:7], 0, s[24:25]
	v_lshl_add_u64 v[6:7], v[6:7], 0, s[24:25]
	s_or_b64 s[26:27], s[6:7], s[26:27]
	s_waitcnt vmcnt(3)
	v_lshlrev_b32_e32 v23, 16, v24
	v_and_b32_e32 v24, 0xffff0000, v24
	v_lshlrev_b32_e32 v29, 16, v26
	v_lshlrev_b32_e32 v28, 16, v25
	v_and_b32_e32 v31, 0xffff0000, v26
	v_and_b32_e32 v30, 0xffff0000, v25
	v_sub_f32_e32 v23, v23, v24
	v_pk_add_f32 v[24:25], v[28:29], v[30:31] neg_lo:[0,1] neg_hi:[0,1]
	v_add_f32_e32 v0, v0, v23
	v_lshlrev_b32_e32 v26, 16, v27
	v_and_b32_e32 v27, 0xffff0000, v27
	v_add_f32_e32 v0, v24, v0
	v_sub_f32_e32 v26, v26, v27
	v_add_f32_e32 v0, v25, v0
	v_add_f32_e32 v0, v26, v0
	s_waitcnt vmcnt(2)
	v_lshlrev_b32_e32 v23, 16, v32
	v_and_b32_e32 v32, 0xffff0000, v32
	v_lshlrev_b32_e32 v29, 16, v34
	v_lshlrev_b32_e32 v28, 16, v33
	v_and_b32_e32 v31, 0xffff0000, v34
	v_and_b32_e32 v30, 0xffff0000, v33
	v_sub_f32_e32 v23, v23, v32
	v_pk_add_f32 v[32:33], v[28:29], v[30:31] neg_lo:[0,1] neg_hi:[0,1]
	v_add_f32_e32 v0, v0, v23
	v_lshlrev_b32_e32 v34, 16, v35
	v_and_b32_e32 v35, 0xffff0000, v35
	v_add_f32_e32 v0, v32, v0
	v_sub_f32_e32 v34, v34, v35
	v_add_f32_e32 v0, v33, v0
	v_add_f32_e32 v0, v34, v0
	s_waitcnt vmcnt(1)
	v_lshlrev_b32_e32 v23, 16, v36
	v_and_b32_e32 v36, 0xffff0000, v36
	v_lshlrev_b32_e32 v29, 16, v38
	v_lshlrev_b32_e32 v28, 16, v37
	v_and_b32_e32 v31, 0xffff0000, v38
	v_and_b32_e32 v30, 0xffff0000, v37
	v_sub_f32_e32 v23, v23, v36
	v_pk_add_f32 v[36:37], v[28:29], v[30:31] neg_lo:[0,1] neg_hi:[0,1]
	v_add_f32_e32 v0, v0, v23
	v_lshlrev_b32_e32 v38, 16, v39
	v_and_b32_e32 v39, 0xffff0000, v39
	v_add_f32_e32 v0, v36, v0
	v_sub_f32_e32 v38, v38, v39
	v_add_f32_e32 v0, v37, v0
	v_add_f32_e32 v0, v38, v0
	s_waitcnt vmcnt(0)
	v_lshlrev_b32_e32 v23, 16, v40
	v_and_b32_e32 v40, 0xffff0000, v40
	v_lshlrev_b32_e32 v29, 16, v42
	v_lshlrev_b32_e32 v28, 16, v41
	v_and_b32_e32 v31, 0xffff0000, v42
	v_and_b32_e32 v30, 0xffff0000, v41
	v_sub_f32_e32 v23, v23, v40
	v_pk_add_f32 v[40:41], v[28:29], v[30:31] neg_lo:[0,1] neg_hi:[0,1]
	v_add_f32_e32 v0, v0, v23
	v_lshlrev_b32_e32 v42, 16, v43
	v_and_b32_e32 v43, 0xffff0000, v43
	v_add_f32_e32 v0, v40, v0
	v_sub_f32_e32 v42, v42, v43
	v_add_f32_e32 v0, v41, v0
	v_add_f32_e32 v0, v42, v0
	s_andn2_b64 exec, exec, s[26:27]
	s_cbranch_execnz .LBB0_413
	s_or_b64 exec, exec, s[26:27]
	ds_bpermute_b32 v6, v10, v0
	s_waitcnt lgkmcnt(0)
	v_add_f32_e32 v0, v0, v6
	ds_bpermute_b32 v6, v11, v0
	s_waitcnt lgkmcnt(0)
	v_add_f32_e32 v0, v0, v6
	ds_bpermute_b32 v6, v12, v0
	s_waitcnt lgkmcnt(0)
	v_add_f32_e32 v0, v0, v6
	ds_bpermute_b32 v6, v13, v0
	s_waitcnt lgkmcnt(0)
	v_add_f32_e32 v0, v0, v6
	ds_bpermute_b32 v6, v14, v0
	s_waitcnt lgkmcnt(0)
	v_add_f32_e32 v0, v0, v6
	ds_bpermute_b32 v6, v15, v0
	s_and_saveexec_b64 s[6:7], vcc
	s_cbranch_execz .LBB0_407
	s_waitcnt lgkmcnt(0)
	v_add_f32_e32 v0, v0, v6
	v_cndmask_b32_e64 v6, v19, v20, s[4:5]
	v_mul_f32_e32 v6, v6, v0
	v_lshrrev_b32_e32 v0, 1, v21
	v_lshl_add_u64 v[4:5], v[4:5], 0, v[0:1]
	v_lshlrev_b64 v[4:5], 11, v[4:5]
	v_lshlrev_b32_e32 v0, 2, v8
	v_lshl_add_u64 v[4:5], s[10:11], 0, v[4:5]
	v_and_b32_e32 v0, 0x600, v0
	v_lshl_add_u64 v[4:5], v[4:5], 0, v[0:1]
	v_and_b32_e32 v0, 0x7f, v8
	v_lshlrev_b32_e32 v0, 1, v0
	v_lshl_add_u64 v[4:5], v[4:5], 0, v[0:1]
	v_cvt_pk_bf16_f32 v0, v6, v1
	global_store_short v[4:5], v0, off
	global_store_short v[4:5], v1, off offset:256
	s_branch .LBB0_407

; __device__ __forceinline__ unsigned cvt_pk_bf16(float lo, float hi) { unsigned r; asm("v_cvt_pk_bf16_f32 %0, %1, %2" : "=v"(r) : "v"(lo), "v"(hi)); return r; }
; template <int layer>
; __device__ __forceinline__ void run_layer(LAS unsigned char* lds, const XcdBarrier& xb) {
;     ...
;                 for (int job = gw; job < 12 * 512; job += NGW) {
;                     const int seq = job >> 9, ch = job & 511;
;                     const int S = seq < 8 ? 2048 : 4096; const size_t tok0 = seq < 8 ? (size_t)seq * 2048 : (size_t)TP + (size_t)(seq - 8) * 4096;
;                     const bf16_t* fp = FT + (size_t)ch * T + tok0;
;                     float a = 0.f;
;                     for (int s0 = lane * 8; s0 < S; s0 += 512) { const u32x4 v = *(const u32x4*)(fp + s0);
; #pragma unroll
;                         for (int e = 0; e < 4; ++e) a += bf_lo(v[e]) - bf_hi(v[e]); }
;                     a = wave_sum(a) * (S == 2048 ? 0.02209708691207961f : 0.015625f);
;                     if (lane == 0) { bf16_t* o = PQ + (tok0 + S / 2) * 1024 + (ch >> 7) * 256 + (ch & 127); o[0] = (bf16_t)(cvt_pk_bf16(a, 0.f) & 0xffffu); o[128] = 0; }
;                 }
.LBB0_1166:
	global_load_dwordx4 v[24:27], v[6:7], off
	global_load_dwordx4 v[32:35], v[6:7], off offset:1024
	global_load_dwordx4 v[36:39], v[6:7], off offset:2048
	global_load_dwordx4 v[40:43], v[6:7], off offset:3072
	v_add_u32_e32 v22, 0x800, v22
	v_cmp_ge_u32_e64 s[10:11], v22, v21
	v_lshl_add_u64 v[6:7], v[6:7], 0, s[50:51]
	v_lshl_add_u64 v[6:7], v[6:7], 0, s[50:51]
	v_lshl_add_u64 v[6:7], v[6:7], 0, s[50:51]
	v_lshl_add_u64 v[6:7], v[6:7], 0, s[50:51]
	s_or_b64 s[52:53], s[10:11], s[52:53]
	s_waitcnt vmcnt(3)
	v_lshlrev_b32_e32 v23, 16, v24
	v_and_b32_e32 v24, 0xffff0000, v24
	v_lshlrev_b32_e32 v29, 16, v26
	v_lshlrev_b32_e32 v28, 16, v25
	v_and_b32_e32 v31, 0xffff0000, v26
	v_and_b32_e32 v30, 0xffff0000, v25
	v_sub_f32_e32 v23, v23, v24
	v_pk_add_f32 v[24:25], v[28:29], v[30:31] neg_lo:[0,1] neg_hi:[0,1]
	v_add_f32_e32 v0, v0, v23
	v_lshlrev_b32_e32 v26, 16, v27
	v_and_b32_e32 v27, 0xffff0000, v27
	v_add_f32_e32 v0, v24, v0
	v_sub_f32_e32 v26, v26, v27
	v_add_f32_e32 v0, v25, v0
	v_add_f32_e32 v0, v26, v0
	s_waitcnt vmcnt(2)
	v_lshlrev_b32_e32 v23, 16, v32
	v_and_b32_e32 v32, 0xffff0000, v32
	v_lshlrev_b32_e32 v29, 16, v34
	v_lshlrev_b32_e32 v28, 16, v33
	v_and_b32_e32 v31, 0xffff0000, v34
	v_and_b32_e32 v30, 0xffff0000, v33
	v_sub_f32_e32 v23, v23, v32
	v_pk_add_f32 v[32:33], v[28:29], v[30:31] neg_lo:[0,1] neg_hi:[0,1]
	v_add_f32_e32 v0, v0, v23
	v_lshlrev_b32_e32 v34, 16, v35
	v_and_b32_e32 v35, 0xffff0000, v35
	v_add_f32_e32 v0, v32, v0
	v_sub_f32_e32 v34, v34, v35
	v_add_f32_e32 v0, v33, v0
	v_add_f32_e32 v0, v34, v0
	s_waitcnt vmcnt(1)
	v_lshlrev_b32_e32 v23, 16, v36
	v_and_b32_e32 v36, 0xffff0000, v36
	v_lshlrev_b32_e32 v29, 16, v38
	v_lshlrev_b32_e32 v28, 16, v37
	v_and_b32_e32 v31, 0xffff0000, v38
	v_and_b32_e32 v30, 0xffff0000, v37
	v_sub_f32_e32 v23, v23, v36
	v_pk_add_f32 v[36:37], v[28:29], v[30:31] neg_lo:[0,1] neg_hi:[0,1]
	v_add_f32_e32 v0, v0, v23
	v_lshlrev_b32_e32 v38, 16, v39
	v_and_b32_e32 v39, 0xffff0000, v39
	v_add_f32_e32 v0, v36, v0
	v_sub_f32_e32 v38, v38, v39
	v_add_f32_e32 v0, v37, v0
	v_add_f32_e32 v0, v38, v0
	s_waitcnt vmcnt(0)
	v_lshlrev_b32_e32 v23, 16, v40
	v_and_b32_e32 v40, 0xffff0000, v40
	v_lshlrev_b32_e32 v29, 16, v42
	v_lshlrev_b32_e32 v28, 16, v41
	v_and_b32_e32 v31, 0xffff0000, v42
	v_and_b32_e32 v30, 0xffff0000, v41
	v_sub_f32_e32 v23, v23, v40
	v_pk_add_f32 v[40:41], v[28:29], v[30:31] neg_lo:[0,1] neg_hi:[0,1]
	v_add_f32_e32 v0, v0, v23
	v_lshlrev_b32_e32 v42, 16, v43
	v_and_b32_e32 v43, 0xffff0000, v43
	v_add_f32_e32 v0, v40, v0
	v_sub_f32_e32 v42, v42, v43
	v_add_f32_e32 v0, v41, v0
	v_add_f32_e32 v0, v42, v0
	s_andn2_b64 exec, exec, s[52:53]
	s_cbranch_execnz .LBB0_1166
	s_or_b64 exec, exec, s[52:53]
	ds_bpermute_b32 v6, v10, v0
	s_waitcnt lgkmcnt(0)
	v_add_f32_e32 v0, v0, v6
	ds_bpermute_b32 v6, v11, v0
	s_waitcnt lgkmcnt(0)
	v_add_f32_e32 v0, v0, v6
	ds_bpermute_b32 v6, v12, v0
	s_waitcnt lgkmcnt(0)
	v_add_f32_e32 v0, v0, v6
	ds_bpermute_b32 v6, v13, v0
	s_waitcnt lgkmcnt(0)
	v_add_f32_e32 v0, v0, v6
	ds_bpermute_b32 v6, v14, v0
	s_waitcnt lgkmcnt(0)
	v_add_f32_e32 v0, v0, v6
	ds_bpermute_b32 v6, v15, v0
	s_and_saveexec_b64 s[10:11], vcc
	s_cbranch_execz .LBB0_1160
	s_waitcnt lgkmcnt(0)
	v_add_f32_e32 v0, v0, v6
	v_cndmask_b32_e64 v6, v19, v20, s[8:9]
	v_mul_f32_e32 v6, v6, v0
	v_lshrrev_b32_e32 v0, 1, v21
	v_lshl_add_u64 v[4:5], v[4:5], 0, v[0:1]
	v_lshlrev_b64 v[4:5], 11, v[4:5]
	v_lshlrev_b32_e32 v0, 2, v8
	v_lshl_add_u64 v[4:5], s[16:17], 0, v[4:5]
	v_and_b32_e32 v0, 0x600, v0
	v_lshl_add_u64 v[4:5], v[4:5], 0, v[0:1]
	v_and_b32_e32 v0, 0x7f, v8
	v_lshlrev_b32_e32 v0, 1, v0
	v_lshl_add_u64 v[4:5], v[4:5], 0, v[0:1]
	v_cvt_pk_bf16_f32 v0, v6, v1
	global_store_short v[4:5], v0, off
	global_store_short v[4:5], v1, off offset:256
	s_branch .LBB0_1160
